# P1 peeled first iteration: first counted wait tightened to vmcnt(2) so the previous epilogue's store drain is paid before either wave-half starts its MMA phases (instead of stalling the second segment
# baseline (speedup 1.0000x reference)
; #define PG8_STAGE(bufoff, gbase, voff) do { _Pragma("unroll") for (int _i = 0; _i < 2; ++_i) \
;         __builtin_amdgcn_global_load_lds((const unsigned*)((const char*)(gbase) + (voff)[_i]), (PG8_LAS unsigned*)(lds + (bufoff) + ldsw + _i * 8192), 16, 0, 0); } while (0)
; #define PG8_LDA(dst, b, h) do { _Pragma("unroll") for (int m = 0; m < 4; ++m) _Pragma("unroll") for (int k = 0; k < 2; ++k) dst[m][k] = *(const PG8_LAS bf16x8*)(lds + PG8_SA(b, h) + aoff + m * 2048 + k * 1024); } while (0)
; #define PG8_LDB(dst, b, h) do { _Pragma("unroll") for (int n = 0; n < 2; ++n) _Pragma("unroll") for (int k = 0; k < 2; ++k) dst[n][k] = *(const PG8_LAS bf16x8*)(lds + PG8_SB(b, h) + boff + n * 2048 + k * 1024); } while (0)
; #define PG8_MMA(ai, bj, At, Bt) do { __builtin_amdgcn_s_setprio(1); _Pragma("unroll") for (int m = 0; m < 4; ++m) _Pragma("unroll") for (int n = 0; n < 2; ++n) _Pragma("unroll") for (int k = 0; k < 2; ++k) \
;         acc[ai][bj][m][n] = __builtin_amdgcn_mfma_f32_16x16x32_bf16(Bt[n][k], At[m][k], acc[ai][bj][m][n], 0, 0, 0); __builtin_amdgcn_s_setprio(0); } while (0)
; #define PG8_WAIT_V(n) asm volatile("s_waitcnt vmcnt(" #n ")" ::: "memory")
; #define PG8_WAIT_L(n) asm volatile("s_waitcnt lgkmcnt(" #n ")" ::: "memory")
; #define PG8_BAR __builtin_amdgcn_s_barrier()
; template <class Epi, class Sched, bool ALIGN_EPI = false, bool SP2 = false>
; __device__ __forceinline__ void gemm_phase(PG8_LAS unsigned char* lds, const Gemm g, const Sched& S, const Epi& E) {
;     ...
;             const char* a1 = cA + (size_t)(t + 1) * kstep;
;             const char* a2 = last ? nA : cA + (size_t)(t + 2) * kstep; const char* b2 = last ? nB : cB + (size_t)(t + 2) * kstep;
;             const char* a3 = a2 + kstep; const char* b3 = b2 + kstep;
;             if (last && has_next) S.a_ready(nxt);
;             if constexpr (SP2) {
;             PG8_LDB(B0, 0, 0); PG8_LDB(B1, 0, 1); PG8_SCHED; PG8_LDA(At, 0, 0); PG8_STAGE(PG8_SA(1, 1), a1 + hstep, voffA);
;             PG8_WAIT_V(8); PG8_WAIT_L(0); PG8_BAR; PG8_MMA(0, 0, At, B0); PG8_MMA(0, 1, At, B1); PG8_BAR; PG8_SCHED;
;             PG8_LDA(At, 0, 1); PG8_STAGE(PG8_SB(0, 0), b2, voffB); PG8_STAGE(PG8_SB(0, 1), b2 + hstep, voffB); PG8_STAGE(PG8_SA(0, 0), a2, voffA);
;             PG8_WAIT_V(8); PG8_WAIT_L(0); PG8_BAR; PG8_MMA(1, 0, At, B0); PG8_MMA(1, 1, At, B1); PG8_BAR; PG8_SCHED;
.LBB0_142:
	s_ashr_i32 s81, s80, 31
	s_lshl_b64 s[84:85], s[80:81], 19
	s_add_u32 s84, s98, s84
	s_addc_u32 s85, s99, s85
	s_and_b64 s[86:87], s[8:9], exec
	s_cselect_b32 s1, s85, s89
	s_cselect_b32 s11, s84, s88
	s_ashr_i32 s83, s82, 31
	s_lshl_b64 s[86:87], s[82:83], 19
	s_add_u32 s86, s4, s86
	s_addc_u32 s87, s5, s87
	s_and_b64 s[92:93], s[8:9], exec
	s_cselect_b32 s79, s87, s91
	s_cselect_b32 s81, s86, s90
	s_add_u32 s88, s88, 0x40080
	s_addc_u32 s89, s89, 0
	s_add_u32 s83, s90, 0x100
	s_addc_u32 vcc_lo, s91, 0
	s_mov_b32 vcc_hi, -2
	ds_read_b128 v[130:133], v193
	ds_read_b128 v[134:137], v193 offset:1024
	ds_read_b128 v[138:141], v193 offset:2048
	ds_read_b128 v[142:145], v193 offset:3072
	ds_read_b128 v[166:169], v194
	ds_read_b128 v[170:173], v194 offset:1024
	ds_read_b128 v[174:177], v194 offset:2048
	ds_read_b128 v[178:181], v194 offset:3072
	s_add_u32 s90, s88, 0xfffc0080
	s_addc_u32 s91, s89, -1
	s_cmp_eq_u32 vcc_hi, 12
	s_cselect_b32 s93, s1, s91
	s_cselect_b32 s92, s11, s90
	s_cselect_b32 s91, s79, vcc_lo
	s_cselect_b32 s90, s81, s83
	v_lshl_add_u64 v[190:191], s[88:89], 0, v[156:157]
	s_add_i32 m0, s58, 0xc000
	ds_read_b128 v[182:185], v195
	ds_read_b128 v[186:189], v195 offset:1024
	ds_read_b128 v[200:203], v195 offset:2048
	ds_read_b128 v[204:207], v195 offset:3072
	ds_read_b128 v[208:211], v195 offset:4096
	ds_read_b128 v[212:215], v195 offset:5120
	ds_read_b128 v[216:219], v195 offset:6144
	ds_read_b128 v[220:223], v195 offset:7168
	global_load_lds_dwordx4 v[190:191], off
	v_lshl_add_u64 v[190:191], s[88:89], 0, v[158:159]
	s_add_i32 m0, s58, 0xe000
	s_nop 0
	global_load_lds_dwordx4 v[190:191], off
	s_waitcnt vmcnt(2)
	s_waitcnt lgkmcnt(0)
	s_barrier
	s_setprio 1
	s_waitcnt lgkmcnt(0)
	v_mfma_f32_16x16x32_bf16 v[126:129], v[130:133], v[182:185], 0
	v_mfma_f32_16x16x32_bf16 v[122:125], v[138:141], v[182:185], 0
	v_mfma_f32_16x16x32_bf16 v[110:113], v[130:133], v[200:203], 0
	v_mfma_f32_16x16x32_bf16 v[106:109], v[138:141], v[200:203], 0
	v_mfma_f32_16x16x32_bf16 v[94:97], v[130:133], v[208:211], 0
	v_mfma_f32_16x16x32_bf16 v[90:93], v[138:141], v[208:211], 0
	v_mfma_f32_16x16x32_bf16 v[78:81], v[130:133], v[216:219], 0
	v_mfma_f32_16x16x32_bf16 v[74:77], v[138:141], v[216:219], 0
	v_mfma_f32_16x16x32_bf16 v[126:129], v[134:137], v[186:189], v[126:129]
	v_mfma_f32_16x16x32_bf16 v[122:125], v[142:145], v[186:189], v[122:125]
	v_mfma_f32_16x16x32_bf16 v[110:113], v[134:137], v[204:207], v[110:113]
	v_mfma_f32_16x16x32_bf16 v[106:109], v[142:145], v[204:207], v[106:109]
	v_mfma_f32_16x16x32_bf16 v[94:97], v[134:137], v[212:215], v[94:97]
	v_mfma_f32_16x16x32_bf16 v[90:93], v[142:145], v[212:215], v[90:93]
	v_mfma_f32_16x16x32_bf16 v[78:81], v[134:137], v[220:223], v[78:81]
	v_mfma_f32_16x16x32_bf16 v[74:77], v[142:145], v[220:223], v[74:77]
	v_mfma_f32_16x16x32_bf16 v[118:121], v[166:169], v[182:185], 0
	v_mfma_f32_16x16x32_bf16 v[114:117], v[174:177], v[182:185], 0
	v_mfma_f32_16x16x32_bf16 v[102:105], v[166:169], v[200:203], 0
	v_mfma_f32_16x16x32_bf16 v[98:101], v[174:177], v[200:203], 0
	v_mfma_f32_16x16x32_bf16 v[86:89], v[166:169], v[208:211], 0
	v_mfma_f32_16x16x32_bf16 v[82:85], v[174:177], v[208:211], 0
	v_mfma_f32_16x16x32_bf16 v[70:73], v[166:169], v[216:219], 0
	v_mfma_f32_16x16x32_bf16 v[66:69], v[174:177], v[216:219], 0
	v_mfma_f32_16x16x32_bf16 v[118:121], v[170:173], v[186:189], v[118:121]
	v_mfma_f32_16x16x32_bf16 v[114:117], v[178:181], v[186:189], v[114:117]
	v_mfma_f32_16x16x32_bf16 v[102:105], v[170:173], v[204:207], v[102:105]
	v_mfma_f32_16x16x32_bf16 v[98:101], v[178:181], v[204:207], v[98:101]
	v_mfma_f32_16x16x32_bf16 v[86:89], v[170:173], v[212:215], v[86:89]
	v_mfma_f32_16x16x32_bf16 v[82:85], v[178:181], v[212:215], v[82:85]
	v_mfma_f32_16x16x32_bf16 v[70:73], v[170:173], v[220:223], v[70:73]
	v_mfma_f32_16x16x32_bf16 v[66:69], v[178:181], v[220:223], v[66:69]
	s_setprio 0
	s_barrier
	s_add_i32 s94, s7, s97
	v_lshl_add_u64 v[190:191], s[90:91], 0, v[148:149]
	s_mov_b32 m0, s94
	ds_read_b128 v[182:185], v195 offset:16384
	ds_read_b128 v[186:189], v195 offset:17408
	ds_read_b128 v[200:203], v195 offset:18432
	ds_read_b128 v[204:207], v195 offset:19456
	ds_read_b128 v[208:211], v195 offset:20480
	ds_read_b128 v[212:215], v195 offset:21504
	ds_read_b128 v[216:219], v195 offset:22528
	ds_read_b128 v[220:223], v195 offset:23552
	global_load_lds_dwordx4 v[190:191], off
	s_add_i32 m0, s94, 0x2000
	s_add_u32 s94, s90, 0x40000
	v_lshl_add_u64 v[224:225], s[90:91], 0, v[152:153]
	s_addc_u32 s95, s91, 0
	s_add_i32 s18, s64, s97
	global_load_lds_dwordx4 v[224:225], off
	v_lshl_add_u64 v[226:227], s[94:95], 0, v[148:149]
	s_mov_b32 m0, s18
	v_lshl_add_u64 v[228:229], s[92:93], 0, v[150:151]
	global_load_lds_dwordx4 v[226:227], off
	v_lshl_add_u64 v[226:227], s[94:95], 0, v[152:153]
	s_add_i32 m0, s18, 0x2000
	s_nop 0
	global_load_lds_dwordx4 v[226:227], off
	v_lshl_add_u64 v[226:227], s[92:93], 0, v[146:147]
	s_mov_b32 m0, s58
	s_nop 0
	global_load_lds_dwordx4 v[226:227], off
	s_mov_b32 m0, s59
	s_nop 0
	global_load_lds_dwordx4 v[228:229], off
	s_waitcnt vmcnt(8)
	s_waitcnt lgkmcnt(0)
	s_barrier
; #define PG8_STAGE(bufoff, gbase, voff) do { _Pragma("unroll") for (int _i = 0; _i < 2; ++_i) \
;         __builtin_amdgcn_global_load_lds((const unsigned*)((const char*)(gbase) + (voff)[_i]), (PG8_LAS unsigned*)(lds + (bufoff) + ldsw + _i * 8192), 16, 0, 0); } while (0)
; #define PG8_LDA(dst, b, h) do { _Pragma("unroll") for (int m = 0; m < 4; ++m) _Pragma("unroll") for (int k = 0; k < 2; ++k) dst[m][k] = *(const PG8_LAS bf16x8*)(lds + PG8_SA(b, h) + aoff + m * 2048 + k * 1024); } while (0)
; #define PG8_LDB(dst, b, h) do { _Pragma("unroll") for (int n = 0; n < 2; ++n) _Pragma("unroll") for (int k = 0; k < 2; ++k) dst[n][k] = *(const PG8_LAS bf16x8*)(lds + PG8_SB(b, h) + boff + n * 2048 + k * 1024); } while (0)
; #define PG8_MMA(ai, bj, At, Bt) do { __builtin_amdgcn_s_setprio(1); _Pragma("unroll") for (int m = 0; m < 4; ++m) _Pragma("unroll") for (int n = 0; n < 2; ++n) _Pragma("unroll") for (int k = 0; k < 2; ++k) \
;         acc[ai][bj][m][n] = __builtin_amdgcn_mfma_f32_16x16x32_bf16(Bt[n][k], At[m][k], acc[ai][bj][m][n], 0, 0, 0); __builtin_amdgcn_s_setprio(0); } while (0)
; #define PG8_WAIT_V(n) asm volatile("s_waitcnt vmcnt(" #n ")" ::: "memory")
; #define PG8_WAIT_L(n) asm volatile("s_waitcnt lgkmcnt(" #n ")" ::: "memory")
; #define PG8_BAR __builtin_amdgcn_s_barrier()
; #define PG8_SCHED __builtin_amdgcn_sched_barrier(0)
; template <class Epi, class Sched, bool ALIGN_EPI = false, bool SP2 = false>
; __device__ __forceinline__ void gemm_phase(PG8_LAS unsigned char* lds, const Gemm g, const Sched& S, const Epi& E) {
;     ...
;             PG8_WAIT_V(8); PG8_WAIT_L(0); PG8_BAR; PG8_MMA(1, 0, At, B0); PG8_MMA(1, 1, At, B1); PG8_BAR; PG8_SCHED;
;             PG8_LDB(B0, 1, 0); PG8_LDB(B1, 1, 1); PG8_SCHED; PG8_LDA(At, 1, 0); PG8_STAGE(PG8_SA(0, 1), a2 + hstep, voffA);
;             PG8_WAIT_V(8); PG8_WAIT_L(0); PG8_BAR; PG8_MMA(0, 0, At, B0); PG8_MMA(0, 1, At, B1); PG8_BAR; PG8_SCHED;
	s_setprio 1
	s_waitcnt lgkmcnt(0)
	v_mfma_f32_16x16x32_bf16 v[62:65], v[130:133], v[182:185], 0
	v_mfma_f32_16x16x32_bf16 v[58:61], v[138:141], v[182:185], 0
	v_mfma_f32_16x16x32_bf16 v[46:49], v[130:133], v[200:203], 0
	v_mfma_f32_16x16x32_bf16 v[42:45], v[138:141], v[200:203], 0
	v_mfma_f32_16x16x32_bf16 v[30:33], v[130:133], v[208:211], 0
	v_mfma_f32_16x16x32_bf16 v[26:29], v[138:141], v[208:211], 0
	v_mfma_f32_16x16x32_bf16 v[14:17], v[130:133], v[216:219], 0
	v_mfma_f32_16x16x32_bf16 v[10:13], v[138:141], v[216:219], 0
	v_mfma_f32_16x16x32_bf16 v[62:65], v[134:137], v[186:189], v[62:65]
	v_mfma_f32_16x16x32_bf16 v[58:61], v[142:145], v[186:189], v[58:61]
	v_mfma_f32_16x16x32_bf16 v[46:49], v[134:137], v[204:207], v[46:49]
	v_mfma_f32_16x16x32_bf16 v[42:45], v[142:145], v[204:207], v[42:45]
	v_mfma_f32_16x16x32_bf16 v[30:33], v[134:137], v[212:215], v[30:33]
	v_mfma_f32_16x16x32_bf16 v[26:29], v[142:145], v[212:215], v[26:29]
	v_mfma_f32_16x16x32_bf16 v[14:17], v[134:137], v[220:223], v[14:17]
	v_mfma_f32_16x16x32_bf16 v[10:13], v[142:145], v[220:223], v[10:13]
	v_mfma_f32_16x16x32_bf16 v[54:57], v[166:169], v[182:185], 0
	v_mfma_f32_16x16x32_bf16 v[50:53], v[174:177], v[182:185], 0
	v_mfma_f32_16x16x32_bf16 v[38:41], v[166:169], v[200:203], 0
	v_mfma_f32_16x16x32_bf16 v[34:37], v[174:177], v[200:203], 0
	v_mfma_f32_16x16x32_bf16 v[22:25], v[166:169], v[208:211], 0
	v_mfma_f32_16x16x32_bf16 v[18:21], v[174:177], v[208:211], 0
	v_mfma_f32_16x16x32_bf16 v[6:9], v[166:169], v[216:219], 0
	v_mfma_f32_16x16x32_bf16 v[2:5], v[174:177], v[216:219], 0
	v_mfma_f32_16x16x32_bf16 v[54:57], v[170:173], v[186:189], v[54:57]
	v_mfma_f32_16x16x32_bf16 v[50:53], v[178:181], v[186:189], v[50:53]
	v_mfma_f32_16x16x32_bf16 v[38:41], v[170:173], v[204:207], v[38:41]
	v_mfma_f32_16x16x32_bf16 v[34:37], v[178:181], v[204:207], v[34:37]
	v_mfma_f32_16x16x32_bf16 v[22:25], v[170:173], v[212:215], v[22:25]
	v_mfma_f32_16x16x32_bf16 v[18:21], v[178:181], v[212:215], v[18:21]
	v_mfma_f32_16x16x32_bf16 v[6:9], v[170:173], v[220:223], v[6:9]
	v_mfma_f32_16x16x32_bf16 v[2:5], v[178:181], v[220:223], v[2:5]
	s_setprio 0
	s_barrier
	s_add_i32 s18, 0, 0x18000
	s_add_i32 s94, 0, 0x1c000
	v_add_u32_e32 v142, s18, v192
	v_add_u32_e32 v154, s94, v192
	ds_read_b128 v[130:133], v142
	ds_read_b128 v[134:137], v142 offset:1024
	ds_read_b128 v[138:141], v142 offset:2048
	ds_read_b128 v[142:145], v142 offset:3072
	ds_read_b128 v[166:169], v154
	ds_read_b128 v[170:173], v154 offset:1024
	ds_read_b128 v[174:177], v154 offset:2048
	ds_read_b128 v[178:181], v154 offset:3072
	s_add_u32 s92, s92, 0x40000
	s_addc_u32 s93, s93, 0
	s_mov_b32 m0, s56
	v_lshl_add_u64 v[230:231], s[92:93], 0, v[146:147]
	ds_read_b128 v[182:185], v195 offset:32768
	ds_read_b128 v[186:189], v195 offset:33792
	ds_read_b128 v[200:203], v195 offset:34816
	ds_read_b128 v[204:207], v195 offset:35840
	ds_read_b128 v[208:211], v195 offset:36864
	ds_read_b128 v[212:215], v195 offset:37888
	ds_read_b128 v[216:219], v195 offset:38912
	ds_read_b128 v[220:223], v195 offset:39936
	global_load_lds_dwordx4 v[230:231], off
	v_lshl_add_u64 v[230:231], s[92:93], 0, v[150:151]
	s_mov_b32 m0, s57
	s_nop 0
	global_load_lds_dwordx4 v[230:231], off
	s_waitcnt vmcnt(8)
	s_waitcnt lgkmcnt(0)
	s_barrier
	s_setprio 1
	s_waitcnt lgkmcnt(0)
	v_mfma_f32_16x16x32_bf16 v[126:129], v[130:133], v[182:185], v[126:129]
	v_mfma_f32_16x16x32_bf16 v[122:125], v[138:141], v[182:185], v[122:125]
	v_mfma_f32_16x16x32_bf16 v[110:113], v[130:133], v[200:203], v[110:113]
	v_mfma_f32_16x16x32_bf16 v[106:109], v[138:141], v[200:203], v[106:109]
	v_mfma_f32_16x16x32_bf16 v[94:97], v[130:133], v[208:211], v[94:97]
	v_mfma_f32_16x16x32_bf16 v[90:93], v[138:141], v[208:211], v[90:93]
	v_mfma_f32_16x16x32_bf16 v[78:81], v[130:133], v[216:219], v[78:81]
	v_mfma_f32_16x16x32_bf16 v[74:77], v[138:141], v[216:219], v[74:77]
	v_mfma_f32_16x16x32_bf16 v[126:129], v[134:137], v[186:189], v[126:129]
	v_mfma_f32_16x16x32_bf16 v[122:125], v[142:145], v[186:189], v[122:125]
	v_mfma_f32_16x16x32_bf16 v[110:113], v[134:137], v[204:207], v[110:113]
	v_mfma_f32_16x16x32_bf16 v[106:109], v[142:145], v[204:207], v[106:109]
	v_mfma_f32_16x16x32_bf16 v[94:97], v[134:137], v[212:215], v[94:97]
	v_mfma_f32_16x16x32_bf16 v[90:93], v[142:145], v[212:215], v[90:93]
	v_mfma_f32_16x16x32_bf16 v[78:81], v[134:137], v[220:223], v[78:81]
	v_mfma_f32_16x16x32_bf16 v[74:77], v[142:145], v[220:223], v[74:77]
	v_mfma_f32_16x16x32_bf16 v[118:121], v[166:169], v[182:185], v[118:121]
	v_mfma_f32_16x16x32_bf16 v[114:117], v[174:177], v[182:185], v[114:117]
	v_mfma_f32_16x16x32_bf16 v[102:105], v[166:169], v[200:203], v[102:105]
	v_mfma_f32_16x16x32_bf16 v[98:101], v[174:177], v[200:203], v[98:101]
	v_mfma_f32_16x16x32_bf16 v[86:89], v[166:169], v[208:211], v[86:89]
	v_mfma_f32_16x16x32_bf16 v[82:85], v[174:177], v[208:211], v[82:85]
	v_mfma_f32_16x16x32_bf16 v[70:73], v[166:169], v[216:219], v[70:73]
	v_mfma_f32_16x16x32_bf16 v[66:69], v[174:177], v[216:219], v[66:69]
	v_mfma_f32_16x16x32_bf16 v[118:121], v[170:173], v[186:189], v[118:121]
	v_mfma_f32_16x16x32_bf16 v[114:117], v[178:181], v[186:189], v[114:117]
	v_mfma_f32_16x16x32_bf16 v[102:105], v[170:173], v[204:207], v[102:105]
	v_mfma_f32_16x16x32_bf16 v[98:101], v[178:181], v[204:207], v[98:101]
	v_mfma_f32_16x16x32_bf16 v[86:89], v[170:173], v[212:215], v[86:89]
	v_mfma_f32_16x16x32_bf16 v[82:85], v[178:181], v[212:215], v[82:85]
	v_mfma_f32_16x16x32_bf16 v[70:73], v[170:173], v[220:223], v[70:73]
	v_mfma_f32_16x16x32_bf16 v[66:69], v[178:181], v[220:223], v[66:69]
	s_setprio 0
	s_barrier
; #define PG8_STAGE(bufoff, gbase, voff) do { _Pragma("unroll") for (int _i = 0; _i < 2; ++_i) \
;         __builtin_amdgcn_global_load_lds((const unsigned*)((const char*)(gbase) + (voff)[_i]), (PG8_LAS unsigned*)(lds + (bufoff) + ldsw + _i * 8192), 16, 0, 0); } while (0)
; #define PG8_LDA(dst, b, h) do { _Pragma("unroll") for (int m = 0; m < 4; ++m) _Pragma("unroll") for (int k = 0; k < 2; ++k) dst[m][k] = *(const PG8_LAS bf16x8*)(lds + PG8_SA(b, h) + aoff + m * 2048 + k * 1024); } while (0)
; #define PG8_MMA(ai, bj, At, Bt) do { __builtin_amdgcn_s_setprio(1); _Pragma("unroll") for (int m = 0; m < 4; ++m) _Pragma("unroll") for (int n = 0; n < 2; ++n) _Pragma("unroll") for (int k = 0; k < 2; ++k) \
;         acc[ai][bj][m][n] = __builtin_amdgcn_mfma_f32_16x16x32_bf16(Bt[n][k], At[m][k], acc[ai][bj][m][n], 0, 0, 0); __builtin_amdgcn_s_setprio(0); } while (0)
; #define PG8_WAIT_V(n) asm volatile("s_waitcnt vmcnt(" #n ")" ::: "memory")
; #define PG8_WAIT_L(n) asm volatile("s_waitcnt lgkmcnt(" #n ")" ::: "memory")
; #define PG8_BAR __builtin_amdgcn_s_barrier()
; #define PG8_SCHED __builtin_amdgcn_sched_barrier(0)
; template <class Epi, class Sched, bool ALIGN_EPI = false, bool SP2 = false>
; __device__ __forceinline__ void gemm_phase(PG8_LAS unsigned char* lds, const Gemm g, const Sched& S, const Epi& E) {
;     ...
;         for (int t = 0; t < nt; t += 2) {
;     ...
;             PG8_LDA(At, 1, 1); PG8_STAGE(PG8_SB(1, 0), b3, voffB); PG8_STAGE(PG8_SB(1, 1), b3 + hstep, voffB); PG8_STAGE(PG8_SA(1, 0), a3, voffA);
;             PG8_WAIT_V(8); PG8_WAIT_L(0); PG8_BAR; PG8_MMA(1, 0, At, B0); PG8_MMA(1, 1, At, B1); PG8_BAR; PG8_SCHED;
	s_add_i32 s18, s18, s97
	v_lshl_add_u64 v[190:191], v[190:191], 0, s[74:75]
	s_mov_b32 m0, s18
	ds_read_b128 v[182:185], v195 offset:49152
	ds_read_b128 v[186:189], v195 offset:50176
	ds_read_b128 v[200:203], v195 offset:51200
	ds_read_b128 v[204:207], v195 offset:52224
	ds_read_b128 v[208:211], v195 offset:53248
	ds_read_b128 v[212:215], v195 offset:54272
	ds_read_b128 v[216:219], v195 offset:55296
	ds_read_b128 v[220:223], v195 offset:56320
	global_load_lds_dwordx4 v[190:191], off
	s_add_i32 m0, s18, 0x2000
	s_add_u32 s90, s90, 0x40080
	v_lshl_add_u64 v[190:191], v[224:225], 0, s[74:75]
	s_addc_u32 s91, s91, 0
	s_add_i32 s18, s94, s97
	global_load_lds_dwordx4 v[190:191], off
	v_lshl_add_u64 v[190:191], s[90:91], 0, v[148:149]
	s_mov_b32 m0, s18
	s_nop 0
	global_load_lds_dwordx4 v[190:191], off
	v_lshl_add_u64 v[190:191], s[90:91], 0, v[152:153]
	s_add_i32 m0, s18, 0x2000
	s_nop 0
	global_load_lds_dwordx4 v[190:191], off
	v_lshl_add_u64 v[190:191], v[226:227], 0, s[74:75]
	s_mov_b32 m0, s19
	s_nop 0
	global_load_lds_dwordx4 v[190:191], off
	v_lshl_add_u64 v[190:191], v[228:229], 0, s[74:75]
	s_mov_b32 m0, s66
	s_nop 0
	global_load_lds_dwordx4 v[190:191], off
	s_waitcnt vmcnt(8)
	s_waitcnt lgkmcnt(0)
	s_barrier
	s_setprio 1
	s_waitcnt lgkmcnt(0)
	v_mfma_f32_16x16x32_bf16 v[62:65], v[130:133], v[182:185], v[62:65]
	v_mfma_f32_16x16x32_bf16 v[58:61], v[138:141], v[182:185], v[58:61]
	v_mfma_f32_16x16x32_bf16 v[46:49], v[130:133], v[200:203], v[46:49]
	v_mfma_f32_16x16x32_bf16 v[42:45], v[138:141], v[200:203], v[42:45]
	v_mfma_f32_16x16x32_bf16 v[30:33], v[130:133], v[208:211], v[30:33]
	v_mfma_f32_16x16x32_bf16 v[26:29], v[138:141], v[208:211], v[26:29]
	v_mfma_f32_16x16x32_bf16 v[14:17], v[130:133], v[216:219], v[14:17]
	v_mfma_f32_16x16x32_bf16 v[10:13], v[138:141], v[216:219], v[10:13]
	v_mfma_f32_16x16x32_bf16 v[62:65], v[134:137], v[186:189], v[62:65]
	v_mfma_f32_16x16x32_bf16 v[58:61], v[142:145], v[186:189], v[58:61]
	v_mfma_f32_16x16x32_bf16 v[46:49], v[134:137], v[204:207], v[46:49]
	v_mfma_f32_16x16x32_bf16 v[42:45], v[142:145], v[204:207], v[42:45]
	v_mfma_f32_16x16x32_bf16 v[30:33], v[134:137], v[212:215], v[30:33]
	v_mfma_f32_16x16x32_bf16 v[26:29], v[142:145], v[212:215], v[26:29]
	v_mfma_f32_16x16x32_bf16 v[14:17], v[134:137], v[220:223], v[14:17]
	v_mfma_f32_16x16x32_bf16 v[10:13], v[142:145], v[220:223], v[10:13]
	v_mfma_f32_16x16x32_bf16 v[54:57], v[166:169], v[182:185], v[54:57]
	v_mfma_f32_16x16x32_bf16 v[50:53], v[174:177], v[182:185], v[50:53]
	v_mfma_f32_16x16x32_bf16 v[38:41], v[166:169], v[200:203], v[38:41]
	v_mfma_f32_16x16x32_bf16 v[34:37], v[174:177], v[200:203], v[34:37]
	v_mfma_f32_16x16x32_bf16 v[22:25], v[166:169], v[208:211], v[22:25]
	v_mfma_f32_16x16x32_bf16 v[18:21], v[174:177], v[208:211], v[18:21]
	v_mfma_f32_16x16x32_bf16 v[6:9], v[166:169], v[216:219], v[6:9]
	v_mfma_f32_16x16x32_bf16 v[2:5], v[174:177], v[216:219], v[2:5]
	v_mfma_f32_16x16x32_bf16 v[54:57], v[170:173], v[186:189], v[54:57]
	v_mfma_f32_16x16x32_bf16 v[50:53], v[178:181], v[186:189], v[50:53]
	v_mfma_f32_16x16x32_bf16 v[38:41], v[170:173], v[204:207], v[38:41]
	v_mfma_f32_16x16x32_bf16 v[34:37], v[178:181], v[204:207], v[34:37]
	v_mfma_f32_16x16x32_bf16 v[22:25], v[170:173], v[212:215], v[22:25]
	v_mfma_f32_16x16x32_bf16 v[18:21], v[178:181], v[212:215], v[18:21]
	v_mfma_f32_16x16x32_bf16 v[6:9], v[170:173], v[220:223], v[6:9]
	v_mfma_f32_16x16x32_bf16 v[2:5], v[178:181], v[220:223], v[2:5]
	s_setprio 0
	s_barrier
	s_add_i32 vcc_hi, vcc_hi, 2
	s_add_u32 s88, s88, 0x100
	s_addc_u32 s89, s89, 0
	s_add_u32 s83, s83, 0x100
	s_addc_u32 vcc_lo, vcc_lo, 0
	s_cmp_gt_u32 vcc_hi, 13
